# baseline (speedup 1.0000x reference)
; __device__ __forceinline__ unsigned cvt_pk_bf16(float lo, float hi) { f32x2_t v = {lo, hi}; bf16x2_t r = __builtin_convertvector(v, bf16x2_t); return __builtin_bit_cast(unsigned, r); }
; __device__ __forceinline__ void phase0(CParams* pp, LAS unsigned char* lds, int G, int bid, int wave, int lane, int tid) {
;     ...
;     for (int row = gw; row < S; row += NGW) {
;         const f32x4* xr = (const f32x4*)(X + (size_t)row * DM) + lane; u32x2* o8 = (u32x2*)(XB + (size_t)row * DM) + lane;
;         float sq = 0.f;
; #pragma unroll
;         for (int j = 0; j < 8; ++j) { const f32x4 v = xr[64 * j]; sq += (v[0] * v[0] + v[1] * v[1]) + (v[2] * v[2] + v[3] * v[3]);
;             u32x2 w; w.x = pg8::cvt_pk_bf16(v[0], v[1]); w.y = pg8::cvt_pk_bf16(v[2], v[3]); o8[64 * j] = w; }
;         sq = wave_sum(sq);
;         if (lane < 32) ssq[(size_t)row * 32 + lane] = lane == 0 ? sq : 0.f;
.LBB0_31:
	s_waitcnt lgkmcnt(0)
	v_add_co_u32_e32 v10, vcc, 0xfffff000, v6
	v_lshl_add_u64 v[20:21], s[22:23], 0, v[4:5]
	s_nop 0
	v_addc_co_u32_e32 v11, vcc, -1, v7, vcc
	v_add_co_u32_e32 v48, vcc, s3, v20
	s_nop 0
	v_addc_co_u32_e32 v49, vcc, 0, v21, vcc
	global_load_dwordx4 v[16:19], v[10:11], off offset:-3072
	global_load_dwordx4 v[20:23], v[10:11], off offset:-2048
	global_load_dwordx4 v[24:27], v[10:11], off offset:-1024
	global_load_dwordx4 v[28:31], v[6:7], off offset:-4096
	global_load_dwordx4 v[32:35], v[6:7], off offset:-3072
	global_load_dwordx4 v[36:39], v[6:7], off offset:-2048
	global_load_dwordx4 v[40:43], v[6:7], off offset:-1024
	global_load_dwordx4 v[44:47], v[6:7], off
	s_waitcnt vmcnt(0)
	v_cvt_pk_bf16_f32 v10, v16, v17
	v_cvt_pk_bf16_f32 v11, v18, v19
	global_store_dwordx2 v[48:49], v[10:11], off
	v_mul_f32_e32 v1, v17, v17
	v_fmac_f32_e32 v1, v16, v16
	v_mul_f32_e32 v10, v19, v19
	v_fmac_f32_e32 v10, v18, v18
	v_add_f32_e32 v1, v1, v10
	v_cvt_pk_bf16_f32 v10, v20, v21
	v_cvt_pk_bf16_f32 v11, v22, v23
	global_store_dwordx2 v[48:49], v[10:11], off offset:512
	v_mul_f32_e32 v10, v21, v21
	v_mul_f32_e32 v11, v23, v23
	v_fmac_f32_e32 v10, v20, v20
	v_fmac_f32_e32 v11, v22, v22
	v_add_f32_e32 v10, v10, v11
	v_add_f32_e32 v1, v1, v10
	v_cvt_pk_bf16_f32 v10, v24, v25
	v_cvt_pk_bf16_f32 v11, v26, v27
	global_store_dwordx2 v[48:49], v[10:11], off offset:1024
	v_mul_f32_e32 v10, v25, v25
	v_mul_f32_e32 v11, v27, v27
	v_fmac_f32_e32 v10, v24, v24
	v_fmac_f32_e32 v11, v26, v26
	v_add_f32_e32 v10, v10, v11
	v_add_f32_e32 v1, v1, v10
	v_cvt_pk_bf16_f32 v10, v28, v29
	v_cvt_pk_bf16_f32 v11, v30, v31
	global_store_dwordx2 v[48:49], v[10:11], off offset:1536
	v_mul_f32_e32 v10, v29, v29
	v_mul_f32_e32 v11, v31, v31
	v_fmac_f32_e32 v10, v28, v28
	v_fmac_f32_e32 v11, v30, v30
	v_add_f32_e32 v10, v10, v11
	v_add_f32_e32 v1, v1, v10
	v_cvt_pk_bf16_f32 v10, v32, v33
	v_cvt_pk_bf16_f32 v11, v34, v35
	global_store_dwordx2 v[48:49], v[10:11], off offset:2048
	v_mul_f32_e32 v10, v33, v33
	v_mul_f32_e32 v11, v35, v35
	v_fmac_f32_e32 v10, v32, v32
	v_fmac_f32_e32 v11, v34, v34
	v_add_f32_e32 v10, v10, v11
	v_add_f32_e32 v1, v1, v10
	v_cvt_pk_bf16_f32 v10, v36, v37
	v_cvt_pk_bf16_f32 v11, v38, v39
	global_store_dwordx2 v[48:49], v[10:11], off offset:2560
	v_mul_f32_e32 v10, v37, v37
	v_mul_f32_e32 v11, v39, v39
	v_fmac_f32_e32 v10, v36, v36
	v_fmac_f32_e32 v11, v38, v38
	v_add_f32_e32 v10, v10, v11
	v_add_f32_e32 v1, v1, v10
	v_cvt_pk_bf16_f32 v10, v40, v41
	v_cvt_pk_bf16_f32 v11, v42, v43
	global_store_dwordx2 v[48:49], v[10:11], off offset:3072
	v_mul_f32_e32 v10, v41, v41
	v_mul_f32_e32 v11, v43, v43
	v_fmac_f32_e32 v10, v40, v40
	v_fmac_f32_e32 v11, v42, v42
	v_add_f32_e32 v10, v10, v11
	v_add_f32_e32 v1, v1, v10
	v_cvt_pk_bf16_f32 v10, v44, v45
	v_cvt_pk_bf16_f32 v11, v46, v47
	global_store_dwordx2 v[48:49], v[10:11], off offset:3584
	s_nop 1
	v_mul_f32_e32 v10, v45, v45
	v_mul_f32_e32 v11, v47, v47
	v_fmac_f32_e32 v10, v44, v44
	v_fmac_f32_e32 v11, v46, v46
	v_add_f32_e32 v10, v10, v11
	v_add_f32_e32 v1, v1, v10
	ds_bpermute_b32 v10, v8, v1
	s_waitcnt lgkmcnt(0)
	v_add_f32_e32 v1, v1, v10
	ds_bpermute_b32 v10, v9, v1
	s_waitcnt lgkmcnt(0)
	v_add_f32_e32 v1, v1, v10
	ds_bpermute_b32 v10, v12, v1
	s_waitcnt lgkmcnt(0)
	v_add_f32_e32 v1, v1, v10
	ds_bpermute_b32 v10, v13, v1
	s_waitcnt lgkmcnt(0)
	v_add_f32_e32 v1, v1, v10
	ds_bpermute_b32 v10, v14, v1
	s_waitcnt lgkmcnt(0)
	v_add_f32_e32 v1, v1, v10
	ds_bpermute_b32 v10, v15, v1
	s_and_saveexec_b64 s[24:25], s[4:5]
	s_cbranch_execz .LBB0_30
	s_waitcnt lgkmcnt(0)
	v_add_f32_e32 v1, v1, v10
	v_cndmask_b32_e64 v1, 0, v1, s[6:7]
	v_lshl_add_u64 v[10:11], s[22:23], 0, v[2:3]
	global_store_dword v[10:11], v1, off
	s_branch .LBB0_30
